# conversion split plus FF1 epilogue rstd via v_rsq_f32 instead of IEEE sqrt and division expansion (f32, 208 VALU fewer per unit and wave)
# baseline (speedup 1.0000x reference)
.LBB0_1075:
	s_nop 15
	s_nop 15
	v_lshl_add_u32 v8, s6, 8, v1
	v_ashrrev_i32_e32 v9, 31, v8
	v_lshlrev_b64 v[2:3], 7, v[8:9]
	v_lshl_add_u64 v[2:3], v[170:171], 0, v[2:3]
	global_load_dwordx4 v[12:15], v[2:3], off
	global_load_dwordx4 v[16:19], v[2:3], off offset:16
	v_or_b32_e32 v28, 16, v8
	v_ashrrev_i32_e32 v29, 31, v28
	v_lshlrev_b64 v[2:3], 7, v[28:29]
	v_lshl_add_u64 v[24:25], v[170:171], 0, v[2:3]
	global_load_dwordx4 v[2:5], v[24:25], off
	s_lshl_b32 s0, s6, 2
	v_lshl_or_b32 v6, s7, 8, v189
	s_ashr_i32 s1, s6, 5
	s_add_i32 s7, s43, s0
	s_add_i32 s19, s44, s0
	s_cmpk_lt_i32 s6, 0x80
	s_cselect_b32 s0, s1, s7
	s_cselect_b32 s6, s1, s19
	s_ashr_i32 s1, s0, 31
	s_ashr_i32 s7, s6, 31
	s_lshl_b64 s[36:37], s[0:1], 15
	s_lshl_b64 s[0:1], s[6:7], 15
	v_ashrrev_i32_e32 v7, 31, v6
	s_add_u32 s0, s35, s0
	s_addc_u32 s1, s40, s1
	v_lshlrev_b64 v[10:11], 2, v[6:7]
	v_lshl_add_u64 v[26:27], s[0:1], 0, v[10:11]
	global_load_dwordx4 v[20:23], v[26:27], off
	global_load_dwordx4 v[30:33], v[26:27], off offset:16
	global_load_dwordx4 v[180:183], v[26:27], off offset:512
	global_load_dwordx4 v[184:187], v[26:27], off offset:528
	v_lshlrev_b64 v[26:27], 13, v[8:9]
	v_lshl_add_u64 v[26:27], s[10:11], 0, v[26:27]
	v_lshl_add_u64 v[204:205], v[26:27], 0, v[6:7]
	v_mov_b32_e32 v200, 0
	v_mov_b32_e32 v201, 0
	v_mov_b32_e32 v202, 0
	v_mov_b32_e32 v203, 0
	v_lshlrev_b64 v[28:29], 13, v[28:29]
	v_lshl_add_u64 v[28:29], s[10:11], 0, v[28:29]
	v_lshl_add_u64 v[28:29], v[28:29], 0, v[6:7]
	s_waitcnt vmcnt(0)
	v_mov_b32_e32 v196, v12
	v_mov_b32_e32 v197, v16
	v_mov_b32_e32 v16, v13
	v_mov_b32_e32 v12, v14
	v_mov_b32_e32 v13, v18
	v_mov_b32_e32 v18, v15
	v_pk_add_f32 v[14:15], v[196:197], v[16:17]
	global_load_dwordx4 v[196:199], v[24:25], off offset:16
	v_pk_add_f32 v[12:13], v[12:13], v[18:19]
	v_mov_b32_e32 v206, v2
	v_pk_add_f32 v[12:13], v[14:15], v[12:13]
	v_pk_mul_f32 v[24:25], v[22:23], s[16:17] op_sel_hi:[1,0]
	v_add_f32_e32 v9, v12, v13
	ds_bpermute_b32 v12, v238, v9
	v_pk_mul_f32 v[22:23], v[30:31], s[16:17] op_sel_hi:[1,0]
	v_pk_mul_f32 v[26:27], v[20:21], s[16:17] op_sel_hi:[1,0]
	v_pk_mul_f32 v[20:21], v[32:33], s[16:17] op_sel_hi:[1,0]
	v_pk_mul_f32 v[16:17], v[180:181], s[16:17] op_sel_hi:[1,0]
	s_waitcnt lgkmcnt(0)
	v_add_f32_e32 v2, v9, v12
	ds_bpermute_b32 v9, v239, v2
	v_pk_mul_f32 v[14:15], v[182:183], s[16:17] op_sel_hi:[1,0]
	v_pk_mul_f32 v[12:13], v[186:187], s[16:17] op_sel_hi:[1,0]
	s_waitcnt lgkmcnt(0)
	v_add_f32_e32 v2, v2, v9
	v_fmamk_f32 v2, v2, 0x3a000000, v193
	s_waitcnt vmcnt(0)
	v_mov_b32_e32 v207, v196
	v_rsq_f32_e32 v2, v2
	v_mov_b32_e32 v196, v3
	s_nop 1
	s_nop 1
	v_pk_mul_f32 v[18:19], v[184:185], s[16:17] op_sel_hi:[1,0]
	s_nop 0
	s_nop 0
	v_mul_f32_e32 v2, 0x3bb504f3, v2
	v_pk_fma_f32 v[32:33], v[158:159], v[2:3], v[26:27] op_sel_hi:[1,0,1]
	v_pk_fma_f32 v[30:31], v[160:161], v[2:3], v[24:25] op_sel_hi:[1,0,1]
	v_med3_f32 v32, v32, 0, v195
	v_med3_f32 v33, v33, 0, v195
	v_pk_mul_f32 v[32:33], v[32:33], v[32:33]
	v_med3_f32 v30, v30, 0, v195
	v_cvt_pk_fp8_f32 v200, v32, v33
	v_med3_f32 v31, v31, 0, v195
	v_pk_fma_f32 v[154:155], v[154:155], v[2:3], v[22:23] op_sel_hi:[1,0,1]
	v_pk_mul_f32 v[30:31], v[30:31], v[30:31]
	v_pk_fma_f32 v[150:151], v[150:151], v[2:3], v[16:17] op_sel_hi:[1,0,1]
	v_pk_fma_f32 v[146:147], v[146:147], v[2:3], v[18:19] op_sel_hi:[1,0,1]
	v_med3_f32 v154, v154, 0, v195
	v_med3_f32 v155, v155, 0, v195
	v_cvt_pk_fp8_f32 v200, v30, v31 op_sel:[0,0,1]
	v_mov_b32_e32 v30, v4
	v_mov_b32_e32 v31, v198
	v_mov_b32_e32 v198, v5
	v_pk_fma_f32 v[156:157], v[156:157], v[2:3], v[20:21] op_sel_hi:[1,0,1]
	v_pk_fma_f32 v[152:153], v[152:153], v[2:3], v[14:15] op_sel_hi:[1,0,1]
	v_pk_fma_f32 v[148:149], v[148:149], v[2:3], v[12:13] op_sel_hi:[1,0,1]
	v_med3_f32 v150, v150, 0, v195
	v_med3_f32 v146, v146, 0, v195
	v_med3_f32 v151, v151, 0, v195
	v_med3_f32 v147, v147, 0, v195
	v_pk_mul_f32 v[154:155], v[154:155], v[154:155]
	v_pk_add_f32 v[2:3], v[206:207], v[196:197]
	v_pk_add_f32 v[4:5], v[30:31], v[198:199]
	v_pk_mul_f32 v[150:151], v[150:151], v[150:151]
	v_pk_mul_f32 v[146:147], v[146:147], v[146:147]
	v_cvt_pk_fp8_f32 v201, v154, v155
	v_pk_add_f32 v[2:3], v[2:3], v[4:5]
	v_cvt_pk_fp8_f32 v202, v150, v151
	v_cvt_pk_fp8_f32 v203, v146, v147
	v_add_f32_e32 v2, v2, v3
	v_med3_f32 v156, v156, 0, v195
	v_med3_f32 v157, v157, 0, v195
	ds_bpermute_b32 v3, v238, v2
	v_med3_f32 v152, v152, 0, v195
	v_med3_f32 v148, v148, 0, v195
	v_med3_f32 v153, v153, 0, v195
	v_med3_f32 v149, v149, 0, v195
	v_pk_mul_f32 v[156:157], v[156:157], v[156:157]
	v_pk_mul_f32 v[152:153], v[152:153], v[152:153]
	v_pk_mul_f32 v[148:149], v[148:149], v[148:149]
	v_cvt_pk_fp8_f32 v201, v156, v157 op_sel:[0,0,1]
	v_cvt_pk_fp8_f32 v202, v152, v153 op_sel:[0,0,1]
	v_cvt_pk_fp8_f32 v203, v148, v149 op_sel:[0,0,1]
	v_or_b32_e32 v146, 32, v8
	v_ashrrev_i32_e32 v147, 31, v146
	s_waitcnt lgkmcnt(0)
	v_add_f32_e32 v9, v2, v3
	v_lshlrev_b64 v[2:3], 7, v[146:147]
	global_store_dwordx2 v[204:205], v[200:201], off
	global_store_dwordx2 v[204:205], v[202:203], off offset:128
	v_lshl_add_u64 v[30:31], v[170:171], 0, v[2:3]
	global_load_dwordx4 v[2:5], v[30:31], off
	s_nop 0
	global_load_dwordx4 v[30:33], v[30:31], off offset:16
	ds_bpermute_b32 v148, v239, v9
	s_waitcnt lgkmcnt(0)
	v_add_f32_e32 v9, v9, v148
	v_fmamk_f32 v9, v9, 0x3a000000, v193
	s_nop 1
	v_rsq_f32_e32 v9, v9
	s_nop 0
	s_nop 0
	s_nop 1
	s_nop 1
	s_nop 0
	s_nop 0
	v_mul_f32_e32 v148, 0x3bb504f3, v9
	v_pk_fma_f32 v[142:143], v[142:143], v[148:149], v[26:27] op_sel_hi:[1,0,1]
	v_mov_b32_e32 v150, 0
	v_med3_f32 v142, v142, 0, v195
	v_med3_f32 v143, v143, 0, v195
	v_pk_mul_f32 v[142:143], v[142:143], v[142:143]
	v_pk_fma_f32 v[138:139], v[138:139], v[148:149], v[22:23] op_sel_hi:[1,0,1]
	v_cvt_pk_fp8_f32 v150, v142, v143
	v_pk_fma_f32 v[144:145], v[144:145], v[148:149], v[24:25] op_sel_hi:[1,0,1]
	v_med3_f32 v138, v138, 0, v195
	v_med3_f32 v139, v139, 0, v195
	v_med3_f32 v144, v144, 0, v195
	v_med3_f32 v145, v145, 0, v195
	v_pk_mul_f32 v[138:139], v[138:139], v[138:139]
	v_mov_b32_e32 v151, 0
	v_pk_fma_f32 v[130:131], v[130:131], v[148:149], v[18:19] op_sel_hi:[1,0,1]
	v_cvt_pk_fp8_f32 v151, v138, v139
	v_pk_mul_f32 v[138:139], v[144:145], v[144:145]
	v_med3_f32 v130, v130, 0, v195
	v_med3_f32 v131, v131, 0, v195
	v_cvt_pk_fp8_f32 v150, v138, v139 op_sel:[0,0,1]
	v_pk_mul_f32 v[130:131], v[130:131], v[130:131]
	v_mov_b32_e32 v139, 0
	v_cvt_pk_fp8_f32 v139, v130, v131
	v_pk_fma_f32 v[134:135], v[134:135], v[148:149], v[16:17] op_sel_hi:[1,0,1]
	v_mov_b32_e32 v138, 0
	v_med3_f32 v134, v134, 0, v195
	v_med3_f32 v135, v135, 0, v195
	v_pk_mul_f32 v[134:135], v[134:135], v[134:135]
	s_waitcnt vmcnt(1)
	v_mov_b32_e32 v130, v2
	s_waitcnt vmcnt(0)
	v_mov_b32_e32 v131, v30
	v_mov_b32_e32 v30, v3
	v_pk_add_f32 v[2:3], v[130:131], v[30:31]
	v_mov_b32_e32 v30, v4
	v_mov_b32_e32 v31, v32
	v_mov_b32_e32 v32, v5
	v_pk_add_f32 v[4:5], v[30:31], v[32:33]
	v_cvt_pk_fp8_f32 v138, v134, v135
	v_pk_add_f32 v[2:3], v[2:3], v[4:5]
	v_pk_fma_f32 v[140:141], v[140:141], v[148:149], v[20:21] op_sel_hi:[1,0,1]
	v_add_f32_e32 v4, v2, v3
	ds_bpermute_b32 v5, v238, v4
	v_pk_fma_f32 v[136:137], v[136:137], v[148:149], v[14:15] op_sel_hi:[1,0,1]
	v_pk_fma_f32 v[132:133], v[132:133], v[148:149], v[12:13] op_sel_hi:[1,0,1]
	v_med3_f32 v140, v140, 0, v195
	v_med3_f32 v141, v141, 0, v195
	s_waitcnt lgkmcnt(0)
	v_add_f32_e32 v4, v4, v5
	ds_bpermute_b32 v5, v239, v4
	v_med3_f32 v136, v136, 0, v195
	v_med3_f32 v132, v132, 0, v195
	v_med3_f32 v137, v137, 0, v195
	v_med3_f32 v133, v133, 0, v195
	v_pk_mul_f32 v[140:141], v[140:141], v[140:141]
	v_pk_mul_f32 v[136:137], v[136:137], v[136:137]
	v_pk_mul_f32 v[2:3], v[132:133], v[132:133]
	v_cvt_pk_fp8_f32 v151, v140, v141 op_sel:[0,0,1]
	v_cvt_pk_fp8_f32 v138, v136, v137 op_sel:[0,0,1]
	v_cvt_pk_fp8_f32 v139, v2, v3 op_sel:[0,0,1]
	v_or_b32_e32 v32, 48, v8
	v_ashrrev_i32_e32 v33, 31, v32
	s_waitcnt lgkmcnt(0)
	v_add_f32_e32 v4, v4, v5
	v_lshlrev_b64 v[2:3], 7, v[32:33]
	v_fmamk_f32 v4, v4, 0x3a000000, v193
	global_store_dwordx2 v[28:29], v[150:151], off
	global_store_dwordx2 v[28:29], v[138:139], off offset:128
	v_lshl_add_u64 v[28:29], v[170:171], 0, v[2:3]
	s_nop 0
	v_rsq_f32_e32 v9, v4
	global_load_dwordx4 v[2:5], v[28:29], off
	s_nop 0
	global_load_dwordx4 v[28:31], v[28:29], off offset:16
	s_nop 0
	s_nop 0
	s_nop 1
	s_nop 1
	v_lshlrev_b64 v[130:131], 13, v[146:147]
	s_add_u32 s0, s35, s36
	s_addc_u32 s1, s40, s37
	s_nop 0
	v_mul_f32_e32 v132, 0x3bb504f3, v9
	v_pk_fma_f32 v[126:127], v[126:127], v[132:133], v[26:27] op_sel_hi:[1,0,1]
	v_mov_b32_e32 v134, 0
	v_med3_f32 v126, v126, 0, v195
	v_med3_f32 v127, v127, 0, v195
	v_pk_mul_f32 v[126:127], v[126:127], v[126:127]
	v_pk_fma_f32 v[122:123], v[122:123], v[132:133], v[22:23] op_sel_hi:[1,0,1]
	v_cvt_pk_fp8_f32 v134, v126, v127
	v_pk_fma_f32 v[128:129], v[128:129], v[132:133], v[24:25] op_sel_hi:[1,0,1]
	v_med3_f32 v122, v122, 0, v195
	v_med3_f32 v123, v123, 0, v195
	v_med3_f32 v128, v128, 0, v195
	v_med3_f32 v129, v129, 0, v195
	v_pk_mul_f32 v[122:123], v[122:123], v[122:123]
	v_mov_b32_e32 v135, 0
	v_pk_fma_f32 v[118:119], v[118:119], v[132:133], v[16:17] op_sel_hi:[1,0,1]
	v_pk_fma_f32 v[114:115], v[114:115], v[132:133], v[18:19] op_sel_hi:[1,0,1]
	v_cvt_pk_fp8_f32 v135, v122, v123
	v_pk_mul_f32 v[122:123], v[128:129], v[128:129]
	v_med3_f32 v118, v118, 0, v195
	v_med3_f32 v114, v114, 0, v195
	v_med3_f32 v119, v119, 0, v195
	v_med3_f32 v115, v115, 0, v195
	v_cvt_pk_fp8_f32 v134, v122, v123 op_sel:[0,0,1]
	v_pk_mul_f32 v[118:119], v[118:119], v[118:119]
	v_pk_mul_f32 v[114:115], v[114:115], v[114:115]
	v_mov_b32_e32 v122, 0
	v_mov_b32_e32 v123, 0
	v_pk_fma_f32 v[124:125], v[124:125], v[132:133], v[20:21] op_sel_hi:[1,0,1]
	v_cvt_pk_fp8_f32 v122, v118, v119
	v_cvt_pk_fp8_f32 v123, v114, v115
	v_med3_f32 v124, v124, 0, v195
	v_med3_f32 v125, v125, 0, v195
	v_pk_fma_f32 v[120:121], v[120:121], v[132:133], v[14:15] op_sel_hi:[1,0,1]
	v_pk_fma_f32 v[116:117], v[116:117], v[132:133], v[12:13] op_sel_hi:[1,0,1]
	v_pk_mul_f32 v[124:125], v[124:125], v[124:125]
	v_med3_f32 v120, v120, 0, v195
	v_med3_f32 v116, v116, 0, v195
	v_med3_f32 v121, v121, 0, v195
	v_med3_f32 v117, v117, 0, v195
	v_cvt_pk_fp8_f32 v135, v124, v125 op_sel:[0,0,1]
	v_pk_mul_f32 v[114:115], v[120:121], v[120:121]
	v_pk_mul_f32 v[116:117], v[116:117], v[116:117]
	v_cvt_pk_fp8_f32 v122, v114, v115 op_sel:[0,0,1]
	v_cvt_pk_fp8_f32 v123, v116, v117 op_sel:[0,0,1]
	v_lshl_add_u64 v[114:115], s[10:11], 0, v[130:131]
	v_lshl_add_u64 v[114:115], v[114:115], 0, v[6:7]
	global_store_dwordx2 v[114:115], v[134:135], off
	global_store_dwordx2 v[114:115], v[122:123], off offset:128
	s_waitcnt vmcnt(3)
	v_mov_b32_e32 v114, v2
	s_waitcnt vmcnt(2)
	v_mov_b32_e32 v115, v28
	v_mov_b32_e32 v28, v3
	v_pk_add_f32 v[2:3], v[114:115], v[28:29]
	v_mov_b32_e32 v28, v4
	v_mov_b32_e32 v29, v30
	v_mov_b32_e32 v30, v5
	v_pk_add_f32 v[4:5], v[28:29], v[30:31]
	v_add_u32_e32 v130, 0x80, v8
	v_pk_add_f32 v[2:3], v[2:3], v[4:5]
	v_ashrrev_i32_e32 v131, 31, v130
	v_add_f32_e32 v4, v2, v3
	ds_bpermute_b32 v5, v238, v4
	v_lshlrev_b64 v[2:3], 7, v[130:131]
	v_lshl_add_u64 v[28:29], v[170:171], 0, v[2:3]
	v_lshl_add_u64 v[10:11], s[0:1], 0, v[10:11]
	s_waitcnt lgkmcnt(0)
	v_add_f32_e32 v9, v4, v5
	global_load_dwordx4 v[2:5], v[28:29], off
	s_nop 0
	global_load_dwordx4 v[28:31], v[28:29], off offset:16
	ds_bpermute_b32 v114, v239, v9
	s_waitcnt lgkmcnt(0)
	v_add_f32_e32 v9, v9, v114
	v_fmamk_f32 v9, v9, 0x3a000000, v193
	s_nop 1
	v_rsq_f32_e32 v9, v9
	global_load_dwordx4 v[114:117], v[10:11], off offset:16
	global_load_dwordx4 v[118:121], v[10:11], off
	s_nop 0
	s_nop 1
	s_nop 1
	global_load_dwordx4 v[122:125], v[10:11], off offset:528
	global_load_dwordx4 v[126:129], v[10:11], off offset:512
	v_lshlrev_b64 v[10:11], 13, v[32:33]
	s_nop 0
	v_mul_f32_e32 v32, 0x3bb504f3, v9
	v_pk_fma_f32 v[22:23], v[106:107], v[32:33], v[22:23] op_sel_hi:[1,0,1]
	v_mov_b32_e32 v107, 0
	v_med3_f32 v22, v22, 0, v195
	v_med3_f32 v23, v23, 0, v195
	v_pk_mul_f32 v[22:23], v[22:23], v[22:23]
	v_pk_fma_f32 v[20:21], v[108:109], v[32:33], v[20:21] op_sel_hi:[1,0,1]
	v_cvt_pk_fp8_f32 v107, v22, v23
	v_med3_f32 v20, v20, 0, v195
	v_med3_f32 v21, v21, 0, v195
	v_pk_fma_f32 v[18:19], v[98:99], v[32:33], v[18:19] op_sel_hi:[1,0,1]
	v_pk_mul_f32 v[20:21], v[20:21], v[20:21]
	v_med3_f32 v18, v18, 0, v195
	v_med3_f32 v19, v19, 0, v195
	v_pk_fma_f32 v[26:27], v[110:111], v[32:33], v[26:27] op_sel_hi:[1,0,1]
	v_cvt_pk_fp8_f32 v107, v20, v21 op_sel:[0,0,1]
	v_pk_mul_f32 v[18:19], v[18:19], v[18:19]
	v_mov_b32_e32 v21, 0
	v_med3_f32 v26, v26, 0, v195
	v_med3_f32 v27, v27, 0, v195
	v_pk_fma_f32 v[16:17], v[102:103], v[32:33], v[16:17] op_sel_hi:[1,0,1]
	v_cvt_pk_fp8_f32 v21, v18, v19
	v_pk_mul_f32 v[26:27], v[26:27], v[26:27]
	v_mov_b32_e32 v106, 0
	v_pk_fma_f32 v[12:13], v[100:101], v[32:33], v[12:13] op_sel_hi:[1,0,1]
	v_med3_f32 v16, v16, 0, v195
	v_med3_f32 v17, v17, 0, v195
	v_cvt_pk_fp8_f32 v106, v26, v27
	v_med3_f32 v12, v12, 0, v195
	v_med3_f32 v13, v13, 0, v195
	v_pk_mul_f32 v[16:17], v[16:17], v[16:17]
	v_mov_b32_e32 v20, 0
	v_pk_fma_f32 v[24:25], v[112:113], v[32:33], v[24:25] op_sel_hi:[1,0,1]
	v_cvt_pk_fp8_f32 v20, v16, v17
	v_pk_mul_f32 v[12:13], v[12:13], v[12:13]
	v_med3_f32 v24, v24, 0, v195
	v_med3_f32 v25, v25, 0, v195
	v_pk_fma_f32 v[14:15], v[104:105], v[32:33], v[14:15] op_sel_hi:[1,0,1]
	v_cvt_pk_fp8_f32 v21, v12, v13 op_sel:[0,0,1]
	s_waitcnt vmcnt(5)
	v_mov_b32_e32 v12, v2
	s_waitcnt vmcnt(4)
	v_mov_b32_e32 v13, v28
	v_mov_b32_e32 v28, v3
	v_pk_mul_f32 v[22:23], v[24:25], v[24:25]
	v_med3_f32 v14, v14, 0, v195
	v_med3_f32 v15, v15, 0, v195
	v_pk_add_f32 v[2:3], v[12:13], v[28:29]
	v_mov_b32_e32 v12, v4
	v_mov_b32_e32 v13, v30
	v_mov_b32_e32 v30, v5
	v_cvt_pk_fp8_f32 v106, v22, v23 op_sel:[0,0,1]
	v_pk_mul_f32 v[14:15], v[14:15], v[14:15]
	v_pk_add_f32 v[4:5], v[12:13], v[30:31]
	v_cvt_pk_fp8_f32 v20, v14, v15 op_sel:[0,0,1]
	v_pk_add_f32 v[2:3], v[2:3], v[4:5]
	v_add_u32_e32 v30, 0x90, v8
	v_add_f32_e32 v4, v2, v3
	v_lshl_add_u64 v[2:3], s[10:11], 0, v[10:11]
	v_lshl_add_u64 v[2:3], v[2:3], 0, v[6:7]
	v_ashrrev_i32_e32 v31, 31, v30
	global_store_dwordx2 v[2:3], v[106:107], off
	global_store_dwordx2 v[2:3], v[20:21], off offset:128
	v_lshlrev_b64 v[2:3], 7, v[30:31]
	v_lshl_add_u64 v[2:3], v[170:171], 0, v[2:3]
	global_load_dwordx4 v[22:25], v[2:3], off
	global_load_dwordx4 v[26:29], v[2:3], off offset:16
	ds_bpermute_b32 v5, v238, v4
	s_waitcnt vmcnt(7)
	v_pk_mul_f32 v[12:13], v[114:115], s[16:17] op_sel_hi:[1,0]
	v_lshlrev_b64 v[30:31], 13, v[30:31]
	v_lshl_add_u64 v[30:31], s[10:11], 0, v[30:31]
	s_waitcnt lgkmcnt(0)
	v_add_f32_e32 v4, v4, v5
	ds_bpermute_b32 v5, v239, v4
	v_lshl_add_u64 v[30:31], v[30:31], 0, v[6:7]
	s_waitcnt lgkmcnt(0)
	v_add_f32_e32 v4, v4, v5
	v_fmamk_f32 v4, v4, 0x3a000000, v193
	s_nop 1
	v_rsq_f32_e32 v4, v4
	s_nop 0
	s_nop 0
	s_nop 1
	s_nop 1
	v_lshlrev_b64 v[2:3], 13, v[130:131]
	v_lshl_add_u64 v[2:3], s[10:11], 0, v[2:3]
	v_lshl_add_u64 v[32:33], v[2:3], 0, v[6:7]
	s_nop 0
	v_mov_b32_e32 v2, v4
	v_mul_f32_e32 v98, 0x3bb504f3, v2
	v_pk_fma_f32 v[20:21], v[90:91], v[98:99], v[12:13] op_sel_hi:[1,0,1]
	v_mov_b32_e32 v91, 0
	v_med3_f32 v20, v20, 0, v195
	v_med3_f32 v21, v21, 0, v195
	v_pk_mul_f32 v[20:21], v[20:21], v[20:21]
	s_waitcnt vmcnt(6)
	v_pk_mul_f32 v[4:5], v[118:119], s[16:17] op_sel_hi:[1,0]
	v_cvt_pk_fp8_f32 v91, v20, v21
	s_waitcnt vmcnt(5)
	v_pk_mul_f32 v[20:21], v[122:123], s[16:17] op_sel_hi:[1,0]
	v_pk_mul_f32 v[10:11], v[116:117], s[16:17] op_sel_hi:[1,0]
	v_pk_fma_f32 v[82:83], v[82:83], v[98:99], v[20:21] op_sel_hi:[1,0,1]
	v_pk_fma_f32 v[16:17], v[94:95], v[98:99], v[4:5] op_sel_hi:[1,0,1]
	v_med3_f32 v82, v82, 0, v195
	v_med3_f32 v83, v83, 0, v195
	v_pk_fma_f32 v[18:19], v[92:93], v[98:99], v[10:11] op_sel_hi:[1,0,1]
	v_pk_mul_f32 v[82:83], v[82:83], v[82:83]
	v_mov_b32_e32 v93, 0
	v_med3_f32 v16, v16, 0, v195
	v_med3_f32 v17, v17, 0, v195
	v_cvt_pk_fp8_f32 v93, v82, v83
	v_med3_f32 v18, v18, 0, v195
	v_med3_f32 v19, v19, 0, v195
	v_pk_mul_f32 v[16:17], v[16:17], v[16:17]
	s_waitcnt vmcnt(1)
	v_mov_b32_e32 v82, v22
	s_waitcnt vmcnt(0)
	v_mov_b32_e32 v83, v26
	v_mov_b32_e32 v26, v23
	v_mov_b32_e32 v90, 0
	v_pk_add_f32 v[22:23], v[82:83], v[26:27]
	v_mov_b32_e32 v26, v24
	v_mov_b32_e32 v27, v28
	v_mov_b32_e32 v28, v25
	v_cvt_pk_fp8_f32 v90, v16, v17
	v_pk_mul_f32 v[16:17], v[18:19], v[18:19]
	v_pk_add_f32 v[24:25], v[26:27], v[28:29]
	v_pk_mul_f32 v[2:3], v[120:121], s[16:17] op_sel_hi:[1,0]
	v_cvt_pk_fp8_f32 v91, v16, v17 op_sel:[0,0,1]
	v_pk_mul_f32 v[16:17], v[126:127], s[16:17] op_sel_hi:[1,0]
	v_pk_add_f32 v[22:23], v[22:23], v[24:25]
	v_pk_fma_f32 v[14:15], v[96:97], v[98:99], v[2:3] op_sel_hi:[1,0,1]
	v_pk_fma_f32 v[86:87], v[86:87], v[98:99], v[16:17] op_sel_hi:[1,0,1]
	v_add_f32_e32 v9, v22, v23
	v_med3_f32 v14, v14, 0, v195
	v_med3_f32 v15, v15, 0, v195
	v_med3_f32 v86, v86, 0, v195
	v_med3_f32 v87, v87, 0, v195
	ds_bpermute_b32 v24, v238, v9
	v_pk_mul_f32 v[14:15], v[14:15], v[14:15]
	v_pk_mul_f32 v[86:87], v[86:87], v[86:87]
	v_mov_b32_e32 v92, 0
	v_cvt_pk_fp8_f32 v90, v14, v15 op_sel:[0,0,1]
	v_pk_mul_f32 v[14:15], v[128:129], s[16:17] op_sel_hi:[1,0]
	v_pk_mul_f32 v[18:19], v[124:125], s[16:17] op_sel_hi:[1,0]
	v_cvt_pk_fp8_f32 v92, v86, v87
	v_pk_fma_f32 v[88:89], v[88:89], v[98:99], v[14:15] op_sel_hi:[1,0,1]
	v_pk_fma_f32 v[84:85], v[84:85], v[98:99], v[18:19] op_sel_hi:[1,0,1]
	v_med3_f32 v88, v88, 0, v195
	v_med3_f32 v84, v84, 0, v195
	v_med3_f32 v89, v89, 0, v195
	v_med3_f32 v85, v85, 0, v195
	v_pk_mul_f32 v[88:89], v[88:89], v[88:89]
	v_pk_mul_f32 v[22:23], v[84:85], v[84:85]
	s_waitcnt lgkmcnt(0)
	v_add_f32_e32 v9, v9, v24
	v_cvt_pk_fp8_f32 v92, v88, v89 op_sel:[0,0,1]
	v_cvt_pk_fp8_f32 v93, v22, v23 op_sel:[0,0,1]
	ds_bpermute_b32 v24, v239, v9
	global_store_dwordx2 v[32:33], v[90:91], off
	global_store_dwordx2 v[32:33], v[92:93], off offset:128
	v_add_u32_e32 v32, 0xa0, v8
	v_ashrrev_i32_e32 v33, 31, v32
	s_waitcnt lgkmcnt(0)
	v_add_f32_e32 v9, v9, v24
	v_lshlrev_b64 v[22:23], 7, v[32:33]
	v_fmamk_f32 v9, v9, 0x3a000000, v193
	v_lshl_add_u64 v[26:27], v[170:171], 0, v[22:23]
	v_add_u32_e32 v8, 0xb0, v8
	v_rsq_f32_e32 v9, v9
	global_load_dwordx4 v[22:25], v[26:27], off
	s_nop 0
	global_load_dwordx4 v[26:29], v[26:27], off offset:16
	v_lshlrev_b64 v[32:33], 13, v[32:33]
	v_lshl_add_u64 v[32:33], s[10:11], 0, v[32:33]
	v_lshl_add_u64 v[32:33], v[32:33], 0, v[6:7]
	s_nop 1
	s_nop 1
	s_nop 0
	s_nop 0
	v_mul_f32_e32 v82, 0x3bb504f3, v9
	v_pk_fma_f32 v[78:79], v[78:79], v[82:83], v[4:5] op_sel_hi:[1,0,1]
	v_mov_b32_e32 v84, 0
	v_med3_f32 v78, v78, 0, v195
	v_med3_f32 v79, v79, 0, v195
	v_pk_mul_f32 v[78:79], v[78:79], v[78:79]
	v_pk_fma_f32 v[74:75], v[74:75], v[82:83], v[12:13] op_sel_hi:[1,0,1]
	v_cvt_pk_fp8_f32 v84, v78, v79
	v_pk_fma_f32 v[80:81], v[80:81], v[82:83], v[2:3] op_sel_hi:[1,0,1]
	v_med3_f32 v74, v74, 0, v195
	v_med3_f32 v75, v75, 0, v195
	v_med3_f32 v80, v80, 0, v195
	v_med3_f32 v81, v81, 0, v195
	v_pk_mul_f32 v[74:75], v[74:75], v[74:75]
	v_mov_b32_e32 v85, 0
	v_pk_fma_f32 v[70:71], v[70:71], v[82:83], v[16:17] op_sel_hi:[1,0,1]
	v_pk_fma_f32 v[66:67], v[66:67], v[82:83], v[20:21] op_sel_hi:[1,0,1]
	v_cvt_pk_fp8_f32 v85, v74, v75
	v_pk_mul_f32 v[74:75], v[80:81], v[80:81]
	v_med3_f32 v70, v70, 0, v195
	v_med3_f32 v66, v66, 0, v195
	v_med3_f32 v71, v71, 0, v195
	v_med3_f32 v67, v67, 0, v195
	v_cvt_pk_fp8_f32 v84, v74, v75 op_sel:[0,0,1]
	v_pk_mul_f32 v[70:71], v[70:71], v[70:71]
	v_pk_mul_f32 v[66:67], v[66:67], v[66:67]
	v_mov_b32_e32 v74, 0
	v_mov_b32_e32 v75, 0
	v_pk_fma_f32 v[76:77], v[76:77], v[82:83], v[10:11] op_sel_hi:[1,0,1]
	v_cvt_pk_fp8_f32 v74, v70, v71
	v_cvt_pk_fp8_f32 v75, v66, v67
	v_med3_f32 v76, v76, 0, v195
	v_med3_f32 v77, v77, 0, v195
	v_pk_fma_f32 v[72:73], v[72:73], v[82:83], v[14:15] op_sel_hi:[1,0,1]
	v_pk_fma_f32 v[68:69], v[68:69], v[82:83], v[18:19] op_sel_hi:[1,0,1]
	v_pk_mul_f32 v[76:77], v[76:77], v[76:77]
	v_med3_f32 v72, v72, 0, v195
	v_med3_f32 v68, v68, 0, v195
	v_med3_f32 v73, v73, 0, v195
	v_med3_f32 v69, v69, 0, v195
	v_cvt_pk_fp8_f32 v85, v76, v77 op_sel:[0,0,1]
	v_pk_mul_f32 v[66:67], v[72:73], v[72:73]
	v_pk_mul_f32 v[68:69], v[68:69], v[68:69]
	v_cvt_pk_fp8_f32 v74, v66, v67 op_sel:[0,0,1]
	v_cvt_pk_fp8_f32 v75, v68, v69 op_sel:[0,0,1]
	global_store_dwordx2 v[30:31], v[84:85], off
	global_store_dwordx2 v[30:31], v[74:75], off offset:128
	s_waitcnt vmcnt(3)
	v_mov_b32_e32 v30, v22
	s_waitcnt vmcnt(2)
	v_mov_b32_e32 v31, v26
	v_mov_b32_e32 v26, v23
	v_pk_add_f32 v[22:23], v[30:31], v[26:27]
	v_mov_b32_e32 v26, v24
	v_mov_b32_e32 v27, v28
	v_mov_b32_e32 v28, v25
	v_pk_add_f32 v[24:25], v[26:27], v[28:29]
	v_ashrrev_i32_e32 v9, 31, v8
	v_pk_add_f32 v[22:23], v[22:23], v[24:25]
	s_nop 0
	v_add_f32_e32 v24, v22, v23
	ds_bpermute_b32 v25, v238, v24
	v_lshlrev_b64 v[22:23], 7, v[8:9]
	v_lshl_add_u64 v[26:27], v[170:171], 0, v[22:23]
	v_lshlrev_b64 v[8:9], 13, v[8:9]
	s_waitcnt lgkmcnt(0)
	v_add_f32_e32 v30, v24, v25
	global_load_dwordx4 v[22:25], v[26:27], off
	s_nop 0
	global_load_dwordx4 v[26:29], v[26:27], off offset:16
	ds_bpermute_b32 v31, v239, v30
	s_waitcnt lgkmcnt(0)
	v_add_f32_e32 v30, v30, v31
	v_fmamk_f32 v30, v30, 0x3a000000, v193
	s_nop 1
	v_rsq_f32_e32 v30, v30
	s_nop 0
	s_nop 0
	s_nop 1
	s_nop 1
	s_nop 0
	s_nop 0
	v_mul_f32_e32 v30, 0x3bb504f3, v30
	v_pk_fma_f32 v[56:57], v[56:57], v[30:31], v[14:15] op_sel_hi:[1,0,1]
	v_pk_fma_f32 v[54:55], v[54:55], v[30:31], v[16:17] op_sel_hi:[1,0,1]
	v_pk_fma_f32 v[64:65], v[64:65], v[30:31], v[2:3] op_sel_hi:[1,0,1]
	v_pk_fma_f32 v[62:63], v[62:63], v[30:31], v[4:5] op_sel_hi:[1,0,1]
	v_pk_fma_f32 v[60:61], v[60:61], v[30:31], v[10:11] op_sel_hi:[1,0,1]
	v_pk_fma_f32 v[58:59], v[58:59], v[30:31], v[12:13] op_sel_hi:[1,0,1]
	v_pk_fma_f32 v[52:53], v[52:53], v[30:31], v[18:19] op_sel_hi:[1,0,1]
	v_pk_fma_f32 v[30:31], v[50:51], v[30:31], v[20:21] op_sel_hi:[1,0,1]
	v_med3_f32 v50, v54, 0, v195
	v_med3_f32 v51, v55, 0, v195
	v_med3_f32 v54, v56, 0, v195
	v_med3_f32 v55, v57, 0, v195
	v_med3_f32 v30, v30, 0, v195
	v_med3_f32 v31, v31, 0, v195
	v_med3_f32 v52, v52, 0, v195
	v_med3_f32 v53, v53, 0, v195
	v_med3_f32 v62, v62, 0, v195
	v_med3_f32 v58, v58, 0, v195
	v_med3_f32 v63, v63, 0, v195
	v_med3_f32 v59, v59, 0, v195
	v_pk_mul_f32 v[62:63], v[62:63], v[62:63]
	v_pk_mul_f32 v[58:59], v[58:59], v[58:59]
	v_mov_b32_e32 v66, 0
	v_mov_b32_e32 v67, 0
	v_cvt_pk_fp8_f32 v66, v62, v63
	v_cvt_pk_fp8_f32 v67, v58, v59
	v_med3_f32 v64, v64, 0, v195
	v_med3_f32 v60, v60, 0, v195
	s_waitcnt vmcnt(1)
	v_mov_b32_e32 v56, v22
	s_waitcnt vmcnt(0)
	v_mov_b32_e32 v57, v26
	v_mov_b32_e32 v26, v23
	v_pk_add_f32 v[22:23], v[56:57], v[26:27]
	v_mov_b32_e32 v26, v24
	v_mov_b32_e32 v27, v28
	v_mov_b32_e32 v28, v25
	v_pk_add_f32 v[24:25], v[26:27], v[28:29]
	v_pk_mul_f32 v[26:27], v[30:31], v[30:31]
	v_pk_add_f32 v[22:23], v[22:23], v[24:25]
	v_pk_mul_f32 v[24:25], v[50:51], v[50:51]
	v_add_f32_e32 v28, v22, v23
	ds_bpermute_b32 v29, v238, v28
	v_pk_mul_f32 v[22:23], v[54:55], v[54:55]
	v_med3_f32 v65, v65, 0, v195
	v_med3_f32 v61, v61, 0, v195
	v_pk_mul_f32 v[58:59], v[64:65], v[64:65]
	s_waitcnt lgkmcnt(0)
	v_add_f32_e32 v30, v28, v29
	ds_bpermute_b32 v31, v239, v30
	v_mov_b32_e32 v28, 0
	v_cvt_pk_fp8_f32 v28, v24, v25
	v_mov_b32_e32 v29, 0
	v_cvt_pk_fp8_f32 v29, v26, v27
	s_waitcnt lgkmcnt(0)
	v_add_f32_e32 v24, v30, v31
	v_fmamk_f32 v24, v24, 0x3a000000, v193
	v_cvt_pk_fp8_f32 v28, v22, v23 op_sel:[0,0,1]
	v_pk_mul_f32 v[60:61], v[60:61], v[60:61]
	v_rsq_f32_e32 v26, v24
	v_pk_mul_f32 v[24:25], v[52:53], v[52:53]
	v_cvt_pk_fp8_f32 v66, v58, v59 op_sel:[0,0,1]
	v_cvt_pk_fp8_f32 v29, v24, v25 op_sel:[0,0,1]
	v_cvt_pk_fp8_f32 v67, v60, v61 op_sel:[0,0,1]
	global_store_dwordx2 v[32:33], v[28:29], off offset:128
	global_store_dwordx2 v[32:33], v[66:67], off
	s_nop 0
	s_mov_b64 s[0:1], -1
	s_nop 0
	v_mov_b32_e32 v22, v26
	v_mul_f32_e32 v22, 0x3bb504f3, v22
	v_pk_fma_f32 v[12:13], v[42:43], v[22:23], v[12:13] op_sel_hi:[1,0,1]
	v_pk_fma_f32 v[4:5], v[46:47], v[22:23], v[4:5] op_sel_hi:[1,0,1]
	v_med3_f32 v12, v12, 0, v195
	v_med3_f32 v13, v13, 0, v195
	v_pk_mul_f32 v[12:13], v[12:13], v[12:13]
	v_mov_b32_e32 v25, 0
	v_med3_f32 v4, v4, 0, v195
	v_med3_f32 v5, v5, 0, v195
	v_cvt_pk_fp8_f32 v25, v12, v13
	v_pk_fma_f32 v[10:11], v[44:45], v[22:23], v[10:11] op_sel_hi:[1,0,1]
	v_pk_mul_f32 v[4:5], v[4:5], v[4:5]
	v_mov_b32_e32 v24, 0
	v_med3_f32 v10, v10, 0, v195
	v_med3_f32 v11, v11, 0, v195
	v_cvt_pk_fp8_f32 v24, v4, v5
	v_pk_fma_f32 v[2:3], v[48:49], v[22:23], v[2:3] op_sel_hi:[1,0,1]
	v_pk_mul_f32 v[4:5], v[10:11], v[10:11]
	v_med3_f32 v2, v2, 0, v195
	v_med3_f32 v3, v3, 0, v195
	v_cvt_pk_fp8_f32 v25, v4, v5 op_sel:[0,0,1]
	v_pk_fma_f32 v[4:5], v[38:39], v[22:23], v[16:17] op_sel_hi:[1,0,1]
	v_pk_fma_f32 v[12:13], v[34:35], v[22:23], v[20:21] op_sel_hi:[1,0,1]
	v_pk_mul_f32 v[2:3], v[2:3], v[2:3]
	v_med3_f32 v4, v4, 0, v195
	v_med3_f32 v12, v12, 0, v195
	v_med3_f32 v5, v5, 0, v195
	v_med3_f32 v13, v13, 0, v195
	v_cvt_pk_fp8_f32 v24, v2, v3 op_sel:[0,0,1]
	v_pk_fma_f32 v[2:3], v[40:41], v[22:23], v[14:15] op_sel_hi:[1,0,1]
	v_pk_mul_f32 v[4:5], v[4:5], v[4:5]
	v_pk_mul_f32 v[12:13], v[12:13], v[12:13]
	v_mov_b32_e32 v14, 0
	v_mov_b32_e32 v15, 0
	v_cvt_pk_fp8_f32 v14, v4, v5
	v_cvt_pk_fp8_f32 v15, v12, v13
	v_pk_fma_f32 v[10:11], v[36:37], v[22:23], v[18:19] op_sel_hi:[1,0,1]
	v_med3_f32 v2, v2, 0, v195
	v_med3_f32 v10, v10, 0, v195
	v_med3_f32 v3, v3, 0, v195
	v_med3_f32 v11, v11, 0, v195
	v_pk_mul_f32 v[2:3], v[2:3], v[2:3]
	v_pk_mul_f32 v[4:5], v[10:11], v[10:11]
	v_cvt_pk_fp8_f32 v14, v2, v3 op_sel:[0,0,1]
	v_cvt_pk_fp8_f32 v15, v4, v5 op_sel:[0,0,1]
	v_lshl_add_u64 v[2:3], s[10:11], 0, v[8:9]
	v_lshl_add_u64 v[2:3], v[2:3], 0, v[6:7]
	s_andn2_b64 vcc, exec, s[4:5]
	global_store_dwordx2 v[2:3], v[24:25], off
	global_store_dwordx2 v[2:3], v[14:15], off offset:128
	s_cbranch_vccnz .LBB0_1068
	s_andn2_b64 vcc, exec, s[8:9]
	s_cbranch_vccnz .LBB0_1067
	s_barrier
	s_branch .LBB0_1067
